# prologue x->bf16 pass software-pipelined: four rows in flight per wave with counted waits
# baseline (speedup 1.0000x reference)
.LBB0_972:
	s_waitcnt lgkmcnt(0)
	v_mov_b32_e32 v104, v2
	v_mov_b32_e32 v105, 0
	v_lshlrev_b64 v[98:99], 12, v[104:105]
	v_lshl_add_u64 v[98:99], v[8:9], 0, v[98:99]
	global_load_dwordx4 v[34:37], v[98:99], off
	global_load_dwordx4 v[38:41], v[98:99], off offset:1024
	global_load_dwordx4 v[42:45], v[98:99], off offset:2048
	global_load_dwordx4 v[46:49], v[98:99], off offset:3072
	v_add_u32_e32 v104, s8, v104
	v_mov_b32_e32 v105, 0
	v_lshlrev_b64 v[98:99], 12, v[104:105]
	v_lshl_add_u64 v[98:99], v[8:9], 0, v[98:99]
	global_load_dwordx4 v[50:53], v[98:99], off
	global_load_dwordx4 v[54:57], v[98:99], off offset:1024
	global_load_dwordx4 v[58:61], v[98:99], off offset:2048
	global_load_dwordx4 v[62:65], v[98:99], off offset:3072
	v_add_u32_e32 v104, s8, v104
	v_mov_b32_e32 v105, 0
	v_lshlrev_b64 v[98:99], 12, v[104:105]
	v_lshl_add_u64 v[98:99], v[8:9], 0, v[98:99]
	global_load_dwordx4 v[66:69], v[98:99], off
	global_load_dwordx4 v[70:73], v[98:99], off offset:1024
	global_load_dwordx4 v[74:77], v[98:99], off offset:2048
	global_load_dwordx4 v[78:81], v[98:99], off offset:3072
	v_add_u32_e32 v104, s8, v104
	v_mov_b32_e32 v105, 0
	v_lshlrev_b64 v[98:99], 12, v[104:105]
	v_lshl_add_u64 v[98:99], v[8:9], 0, v[98:99]
	global_load_dwordx4 v[82:85], v[98:99], off
	global_load_dwordx4 v[86:89], v[98:99], off offset:1024
	global_load_dwordx4 v[90:93], v[98:99], off offset:2048
	global_load_dwordx4 v[94:97], v[98:99], off offset:3072
	v_mov_b32_e32 v114, v2
	s_waitcnt vmcnt(12)
	v_mul_f32_e32 v0, v35, v35
	v_fmac_f32_e32 v0, v34, v34
	v_fmac_f32_e32 v0, v36, v36
	v_fmac_f32_e32 v0, v37, v37
	v_cvt_pk_bf16_f32 v106, v34, v35
	v_cvt_pk_bf16_f32 v107, v36, v37
	v_mul_f32_e32 v18, v39, v39
	v_fmac_f32_e32 v18, v38, v38
	v_fmac_f32_e32 v18, v40, v40
	v_fmac_f32_e32 v18, v41, v41
	v_add_f32_e32 v0, v0, v18
	v_cvt_pk_bf16_f32 v108, v38, v39
	v_cvt_pk_bf16_f32 v109, v40, v41
	v_mul_f32_e32 v18, v43, v43
	v_fmac_f32_e32 v18, v42, v42
	v_fmac_f32_e32 v18, v44, v44
	v_fmac_f32_e32 v18, v45, v45
	v_add_f32_e32 v0, v0, v18
	v_cvt_pk_bf16_f32 v110, v42, v43
	v_cvt_pk_bf16_f32 v111, v44, v45
	v_mul_f32_e32 v18, v47, v47
	v_fmac_f32_e32 v18, v46, v46
	v_fmac_f32_e32 v18, v48, v48
	v_fmac_f32_e32 v18, v49, v49
	v_add_f32_e32 v0, v0, v18
	v_cvt_pk_bf16_f32 v112, v46, v47
	v_cvt_pk_bf16_f32 v113, v48, v49
	v_add_u32_e32 v104, s8, v104
	v_mov_b32_e32 v105, 0
	v_lshlrev_b64 v[98:99], 12, v[104:105]
	v_lshl_add_u64 v[98:99], v[8:9], 0, v[98:99]
	global_load_dwordx4 v[34:37], v[98:99], off
	global_load_dwordx4 v[38:41], v[98:99], off offset:1024
	global_load_dwordx4 v[42:45], v[98:99], off offset:2048
	global_load_dwordx4 v[46:49], v[98:99], off offset:3072
	v_mov_b32_e32 v115, 0
	v_lshlrev_b64 v[100:101], 11, v[114:115]
	v_lshl_add_u64 v[100:101], v[4:5], 0, v[100:101]
	global_store_dwordx2 v[100:101], v[106:107], off
	global_store_dwordx2 v[100:101], v[108:109], off offset:512
	global_store_dwordx2 v[100:101], v[110:111], off offset:1024
	global_store_dwordx2 v[100:101], v[112:113], off offset:1536
	ds_bpermute_b32 v16, v10, v0
	s_waitcnt lgkmcnt(0)
	v_add_f32_e32 v0, v0, v16
	ds_bpermute_b32 v16, v11, v0
	s_waitcnt lgkmcnt(0)
	v_add_f32_e32 v0, v0, v16
	ds_bpermute_b32 v16, v12, v0
	s_waitcnt lgkmcnt(0)
	v_add_f32_e32 v0, v0, v16
	ds_bpermute_b32 v16, v13, v0
	s_waitcnt lgkmcnt(0)
	v_add_f32_e32 v0, v0, v16
	ds_bpermute_b32 v16, v14, v0
	s_waitcnt lgkmcnt(0)
	v_add_f32_e32 v0, v0, v16
	ds_bpermute_b32 v16, v15, v0
	s_waitcnt lgkmcnt(0)
	v_add_f32_e32 v0, v0, v16
	v_lshlrev_b64 v[102:103], 6, v[114:115]
	v_cndmask_b32_e64 v0, 0, v0, s[36:37]
	v_lshl_add_u64 v[102:103], v[6:7], 0, v[102:103]
	s_and_saveexec_b64 s[6:7], vcc
	global_store_dword v[102:103], v0, off
	s_or_b64 exec, exec, s[6:7]
	v_add_u32_e32 v114, s8, v114
	s_waitcnt vmcnt(17)
	v_mul_f32_e32 v0, v51, v51
	v_fmac_f32_e32 v0, v50, v50
	v_fmac_f32_e32 v0, v52, v52
	v_fmac_f32_e32 v0, v53, v53
	v_cvt_pk_bf16_f32 v106, v50, v51
	v_cvt_pk_bf16_f32 v107, v52, v53
	v_mul_f32_e32 v18, v55, v55
	v_fmac_f32_e32 v18, v54, v54
	v_fmac_f32_e32 v18, v56, v56
	v_fmac_f32_e32 v18, v57, v57
	v_add_f32_e32 v0, v0, v18
	v_cvt_pk_bf16_f32 v108, v54, v55
	v_cvt_pk_bf16_f32 v109, v56, v57
	v_mul_f32_e32 v18, v59, v59
	v_fmac_f32_e32 v18, v58, v58
	v_fmac_f32_e32 v18, v60, v60
	v_fmac_f32_e32 v18, v61, v61
	v_add_f32_e32 v0, v0, v18
	v_cvt_pk_bf16_f32 v110, v58, v59
	v_cvt_pk_bf16_f32 v111, v60, v61
	v_mul_f32_e32 v18, v63, v63
	v_fmac_f32_e32 v18, v62, v62
	v_fmac_f32_e32 v18, v64, v64
	v_fmac_f32_e32 v18, v65, v65
	v_add_f32_e32 v0, v0, v18
	v_cvt_pk_bf16_f32 v112, v62, v63
	v_cvt_pk_bf16_f32 v113, v64, v65
	v_add_u32_e32 v104, s8, v104
	v_mov_b32_e32 v105, 0
	v_lshlrev_b64 v[98:99], 12, v[104:105]
	v_lshl_add_u64 v[98:99], v[8:9], 0, v[98:99]
	global_load_dwordx4 v[50:53], v[98:99], off
	global_load_dwordx4 v[54:57], v[98:99], off offset:1024
	global_load_dwordx4 v[58:61], v[98:99], off offset:2048
	global_load_dwordx4 v[62:65], v[98:99], off offset:3072
	v_mov_b32_e32 v115, 0
	v_lshlrev_b64 v[100:101], 11, v[114:115]
	v_lshl_add_u64 v[100:101], v[4:5], 0, v[100:101]
	global_store_dwordx2 v[100:101], v[106:107], off
	global_store_dwordx2 v[100:101], v[108:109], off offset:512
	global_store_dwordx2 v[100:101], v[110:111], off offset:1024
	global_store_dwordx2 v[100:101], v[112:113], off offset:1536
	ds_bpermute_b32 v16, v10, v0
	s_waitcnt lgkmcnt(0)
	v_add_f32_e32 v0, v0, v16
	ds_bpermute_b32 v16, v11, v0
	s_waitcnt lgkmcnt(0)
	v_add_f32_e32 v0, v0, v16
	ds_bpermute_b32 v16, v12, v0
	s_waitcnt lgkmcnt(0)
	v_add_f32_e32 v0, v0, v16
	ds_bpermute_b32 v16, v13, v0
	s_waitcnt lgkmcnt(0)
	v_add_f32_e32 v0, v0, v16
	ds_bpermute_b32 v16, v14, v0
	s_waitcnt lgkmcnt(0)
	v_add_f32_e32 v0, v0, v16
	ds_bpermute_b32 v16, v15, v0
	s_waitcnt lgkmcnt(0)
	v_add_f32_e32 v0, v0, v16
	v_lshlrev_b64 v[102:103], 6, v[114:115]
	v_cndmask_b32_e64 v0, 0, v0, s[36:37]
	v_lshl_add_u64 v[102:103], v[6:7], 0, v[102:103]
	s_and_saveexec_b64 s[6:7], vcc
	global_store_dword v[102:103], v0, off
	s_or_b64 exec, exec, s[6:7]
	v_add_u32_e32 v114, s8, v114
	s_waitcnt vmcnt(22)
	v_mul_f32_e32 v0, v67, v67
	v_fmac_f32_e32 v0, v66, v66
	v_fmac_f32_e32 v0, v68, v68
	v_fmac_f32_e32 v0, v69, v69
	v_cvt_pk_bf16_f32 v106, v66, v67
	v_cvt_pk_bf16_f32 v107, v68, v69
	v_mul_f32_e32 v18, v71, v71
	v_fmac_f32_e32 v18, v70, v70
	v_fmac_f32_e32 v18, v72, v72
	v_fmac_f32_e32 v18, v73, v73
	v_add_f32_e32 v0, v0, v18
	v_cvt_pk_bf16_f32 v108, v70, v71
	v_cvt_pk_bf16_f32 v109, v72, v73
	v_mul_f32_e32 v18, v75, v75
	v_fmac_f32_e32 v18, v74, v74
	v_fmac_f32_e32 v18, v76, v76
	v_fmac_f32_e32 v18, v77, v77
	v_add_f32_e32 v0, v0, v18
	v_cvt_pk_bf16_f32 v110, v74, v75
	v_cvt_pk_bf16_f32 v111, v76, v77
	v_mul_f32_e32 v18, v79, v79
	v_fmac_f32_e32 v18, v78, v78
	v_fmac_f32_e32 v18, v80, v80
	v_fmac_f32_e32 v18, v81, v81
	v_add_f32_e32 v0, v0, v18
	v_cvt_pk_bf16_f32 v112, v78, v79
	v_cvt_pk_bf16_f32 v113, v80, v81
	v_add_u32_e32 v104, s8, v104
	v_mov_b32_e32 v105, 0
	v_lshlrev_b64 v[98:99], 12, v[104:105]
	v_lshl_add_u64 v[98:99], v[8:9], 0, v[98:99]
	global_load_dwordx4 v[66:69], v[98:99], off
	global_load_dwordx4 v[70:73], v[98:99], off offset:1024
	global_load_dwordx4 v[74:77], v[98:99], off offset:2048
	global_load_dwordx4 v[78:81], v[98:99], off offset:3072
	v_mov_b32_e32 v115, 0
	v_lshlrev_b64 v[100:101], 11, v[114:115]
	v_lshl_add_u64 v[100:101], v[4:5], 0, v[100:101]
	global_store_dwordx2 v[100:101], v[106:107], off
	global_store_dwordx2 v[100:101], v[108:109], off offset:512
	global_store_dwordx2 v[100:101], v[110:111], off offset:1024
	global_store_dwordx2 v[100:101], v[112:113], off offset:1536
	ds_bpermute_b32 v16, v10, v0
	s_waitcnt lgkmcnt(0)
	v_add_f32_e32 v0, v0, v16
	ds_bpermute_b32 v16, v11, v0
	s_waitcnt lgkmcnt(0)
	v_add_f32_e32 v0, v0, v16
	ds_bpermute_b32 v16, v12, v0
	s_waitcnt lgkmcnt(0)
	v_add_f32_e32 v0, v0, v16
	ds_bpermute_b32 v16, v13, v0
	s_waitcnt lgkmcnt(0)
	v_add_f32_e32 v0, v0, v16
	ds_bpermute_b32 v16, v14, v0
	s_waitcnt lgkmcnt(0)
	v_add_f32_e32 v0, v0, v16
	ds_bpermute_b32 v16, v15, v0
	s_waitcnt lgkmcnt(0)
	v_add_f32_e32 v0, v0, v16
	v_lshlrev_b64 v[102:103], 6, v[114:115]
	v_cndmask_b32_e64 v0, 0, v0, s[36:37]
	v_lshl_add_u64 v[102:103], v[6:7], 0, v[102:103]
	s_and_saveexec_b64 s[6:7], vcc
	global_store_dword v[102:103], v0, off
	s_or_b64 exec, exec, s[6:7]
	v_add_u32_e32 v114, s8, v114
	s_waitcnt vmcnt(27)
	v_mul_f32_e32 v0, v83, v83
	v_fmac_f32_e32 v0, v82, v82
	v_fmac_f32_e32 v0, v84, v84
	v_fmac_f32_e32 v0, v85, v85
	v_cvt_pk_bf16_f32 v106, v82, v83
	v_cvt_pk_bf16_f32 v107, v84, v85
	v_mul_f32_e32 v18, v87, v87
	v_fmac_f32_e32 v18, v86, v86
	v_fmac_f32_e32 v18, v88, v88
	v_fmac_f32_e32 v18, v89, v89
	v_add_f32_e32 v0, v0, v18
	v_cvt_pk_bf16_f32 v108, v86, v87
	v_cvt_pk_bf16_f32 v109, v88, v89
	v_mul_f32_e32 v18, v91, v91
	v_fmac_f32_e32 v18, v90, v90
	v_fmac_f32_e32 v18, v92, v92
	v_fmac_f32_e32 v18, v93, v93
	v_add_f32_e32 v0, v0, v18
	v_cvt_pk_bf16_f32 v110, v90, v91
	v_cvt_pk_bf16_f32 v111, v92, v93
	v_mul_f32_e32 v18, v95, v95
	v_fmac_f32_e32 v18, v94, v94
	v_fmac_f32_e32 v18, v96, v96
	v_fmac_f32_e32 v18, v97, v97
	v_add_f32_e32 v0, v0, v18
	v_cvt_pk_bf16_f32 v112, v94, v95
	v_cvt_pk_bf16_f32 v113, v96, v97
	v_add_u32_e32 v104, s8, v104
	v_mov_b32_e32 v105, 0
	v_lshlrev_b64 v[98:99], 12, v[104:105]
	v_lshl_add_u64 v[98:99], v[8:9], 0, v[98:99]
	global_load_dwordx4 v[82:85], v[98:99], off
	global_load_dwordx4 v[86:89], v[98:99], off offset:1024
	global_load_dwordx4 v[90:93], v[98:99], off offset:2048
	global_load_dwordx4 v[94:97], v[98:99], off offset:3072
	v_mov_b32_e32 v115, 0
	v_lshlrev_b64 v[100:101], 11, v[114:115]
	v_lshl_add_u64 v[100:101], v[4:5], 0, v[100:101]
	global_store_dwordx2 v[100:101], v[106:107], off
	global_store_dwordx2 v[100:101], v[108:109], off offset:512
	global_store_dwordx2 v[100:101], v[110:111], off offset:1024
	global_store_dwordx2 v[100:101], v[112:113], off offset:1536
	ds_bpermute_b32 v16, v10, v0
	s_waitcnt lgkmcnt(0)
	v_add_f32_e32 v0, v0, v16
	ds_bpermute_b32 v16, v11, v0
	s_waitcnt lgkmcnt(0)
	v_add_f32_e32 v0, v0, v16
	ds_bpermute_b32 v16, v12, v0
	s_waitcnt lgkmcnt(0)
	v_add_f32_e32 v0, v0, v16
	ds_bpermute_b32 v16, v13, v0
	s_waitcnt lgkmcnt(0)
	v_add_f32_e32 v0, v0, v16
	ds_bpermute_b32 v16, v14, v0
	s_waitcnt lgkmcnt(0)
	v_add_f32_e32 v0, v0, v16
	ds_bpermute_b32 v16, v15, v0
	s_waitcnt lgkmcnt(0)
	v_add_f32_e32 v0, v0, v16
	v_lshlrev_b64 v[102:103], 6, v[114:115]
	v_cndmask_b32_e64 v0, 0, v0, s[36:37]
	v_lshl_add_u64 v[102:103], v[6:7], 0, v[102:103]
	s_and_saveexec_b64 s[6:7], vcc
	global_store_dword v[102:103], v0, off
	s_or_b64 exec, exec, s[6:7]
	v_add_u32_e32 v114, s8, v114
	s_waitcnt vmcnt(32)
	v_mul_f32_e32 v0, v35, v35
	v_fmac_f32_e32 v0, v34, v34
	v_fmac_f32_e32 v0, v36, v36
	v_fmac_f32_e32 v0, v37, v37
	v_cvt_pk_bf16_f32 v106, v34, v35
	v_cvt_pk_bf16_f32 v107, v36, v37
	v_mul_f32_e32 v18, v39, v39
	v_fmac_f32_e32 v18, v38, v38
	v_fmac_f32_e32 v18, v40, v40
	v_fmac_f32_e32 v18, v41, v41
	v_add_f32_e32 v0, v0, v18
	v_cvt_pk_bf16_f32 v108, v38, v39
	v_cvt_pk_bf16_f32 v109, v40, v41
	v_mul_f32_e32 v18, v43, v43
	v_fmac_f32_e32 v18, v42, v42
	v_fmac_f32_e32 v18, v44, v44
	v_fmac_f32_e32 v18, v45, v45
	v_add_f32_e32 v0, v0, v18
	v_cvt_pk_bf16_f32 v110, v42, v43
	v_cvt_pk_bf16_f32 v111, v44, v45
	v_mul_f32_e32 v18, v47, v47
	v_fmac_f32_e32 v18, v46, v46
	v_fmac_f32_e32 v18, v48, v48
	v_fmac_f32_e32 v18, v49, v49
	v_add_f32_e32 v0, v0, v18
	v_cvt_pk_bf16_f32 v112, v46, v47
	v_cvt_pk_bf16_f32 v113, v48, v49
	v_mov_b32_e32 v115, 0
	v_lshlrev_b64 v[100:101], 11, v[114:115]
	v_lshl_add_u64 v[100:101], v[4:5], 0, v[100:101]
	global_store_dwordx2 v[100:101], v[106:107], off
	global_store_dwordx2 v[100:101], v[108:109], off offset:512
	global_store_dwordx2 v[100:101], v[110:111], off offset:1024
	global_store_dwordx2 v[100:101], v[112:113], off offset:1536
	ds_bpermute_b32 v16, v10, v0
	s_waitcnt lgkmcnt(0)
	v_add_f32_e32 v0, v0, v16
	ds_bpermute_b32 v16, v11, v0
	s_waitcnt lgkmcnt(0)
	v_add_f32_e32 v0, v0, v16
	ds_bpermute_b32 v16, v12, v0
	s_waitcnt lgkmcnt(0)
	v_add_f32_e32 v0, v0, v16
	ds_bpermute_b32 v16, v13, v0
	s_waitcnt lgkmcnt(0)
	v_add_f32_e32 v0, v0, v16
	ds_bpermute_b32 v16, v14, v0
	s_waitcnt lgkmcnt(0)
	v_add_f32_e32 v0, v0, v16
	ds_bpermute_b32 v16, v15, v0
	s_waitcnt lgkmcnt(0)
	v_add_f32_e32 v0, v0, v16
	v_lshlrev_b64 v[102:103], 6, v[114:115]
	v_cndmask_b32_e64 v0, 0, v0, s[36:37]
	v_lshl_add_u64 v[102:103], v[6:7], 0, v[102:103]
	s_and_saveexec_b64 s[6:7], vcc
	global_store_dword v[102:103], v0, off
	s_or_b64 exec, exec, s[6:7]
	v_add_u32_e32 v114, s8, v114
	s_waitcnt vmcnt(28)
	v_mul_f32_e32 v0, v51, v51
	v_fmac_f32_e32 v0, v50, v50
	v_fmac_f32_e32 v0, v52, v52
	v_fmac_f32_e32 v0, v53, v53
	v_cvt_pk_bf16_f32 v106, v50, v51
	v_cvt_pk_bf16_f32 v107, v52, v53
	v_mul_f32_e32 v18, v55, v55
	v_fmac_f32_e32 v18, v54, v54
	v_fmac_f32_e32 v18, v56, v56
	v_fmac_f32_e32 v18, v57, v57
	v_add_f32_e32 v0, v0, v18
	v_cvt_pk_bf16_f32 v108, v54, v55
	v_cvt_pk_bf16_f32 v109, v56, v57
	v_mul_f32_e32 v18, v59, v59
	v_fmac_f32_e32 v18, v58, v58
	v_fmac_f32_e32 v18, v60, v60
	v_fmac_f32_e32 v18, v61, v61
	v_add_f32_e32 v0, v0, v18
	v_cvt_pk_bf16_f32 v110, v58, v59
	v_cvt_pk_bf16_f32 v111, v60, v61
	v_mul_f32_e32 v18, v63, v63
	v_fmac_f32_e32 v18, v62, v62
	v_fmac_f32_e32 v18, v64, v64
	v_fmac_f32_e32 v18, v65, v65
	v_add_f32_e32 v0, v0, v18
	v_cvt_pk_bf16_f32 v112, v62, v63
	v_cvt_pk_bf16_f32 v113, v64, v65
	v_mov_b32_e32 v115, 0
	v_lshlrev_b64 v[100:101], 11, v[114:115]
	v_lshl_add_u64 v[100:101], v[4:5], 0, v[100:101]
	global_store_dwordx2 v[100:101], v[106:107], off
	global_store_dwordx2 v[100:101], v[108:109], off offset:512
	global_store_dwordx2 v[100:101], v[110:111], off offset:1024
	global_store_dwordx2 v[100:101], v[112:113], off offset:1536
	ds_bpermute_b32 v16, v10, v0
	s_waitcnt lgkmcnt(0)
	v_add_f32_e32 v0, v0, v16
	ds_bpermute_b32 v16, v11, v0
	s_waitcnt lgkmcnt(0)
	v_add_f32_e32 v0, v0, v16
	ds_bpermute_b32 v16, v12, v0
	s_waitcnt lgkmcnt(0)
	v_add_f32_e32 v0, v0, v16
	ds_bpermute_b32 v16, v13, v0
	s_waitcnt lgkmcnt(0)
	v_add_f32_e32 v0, v0, v16
	ds_bpermute_b32 v16, v14, v0
	s_waitcnt lgkmcnt(0)
	v_add_f32_e32 v0, v0, v16
	ds_bpermute_b32 v16, v15, v0
	s_waitcnt lgkmcnt(0)
	v_add_f32_e32 v0, v0, v16
	v_lshlrev_b64 v[102:103], 6, v[114:115]
	v_cndmask_b32_e64 v0, 0, v0, s[36:37]
	v_lshl_add_u64 v[102:103], v[6:7], 0, v[102:103]
	s_and_saveexec_b64 s[6:7], vcc
	global_store_dword v[102:103], v0, off
	s_or_b64 exec, exec, s[6:7]
	v_add_u32_e32 v114, s8, v114
	s_waitcnt vmcnt(24)
	v_mul_f32_e32 v0, v67, v67
	v_fmac_f32_e32 v0, v66, v66
	v_fmac_f32_e32 v0, v68, v68
	v_fmac_f32_e32 v0, v69, v69
	v_cvt_pk_bf16_f32 v106, v66, v67
	v_cvt_pk_bf16_f32 v107, v68, v69
	v_mul_f32_e32 v18, v71, v71
	v_fmac_f32_e32 v18, v70, v70
	v_fmac_f32_e32 v18, v72, v72
	v_fmac_f32_e32 v18, v73, v73
	v_add_f32_e32 v0, v0, v18
	v_cvt_pk_bf16_f32 v108, v70, v71
	v_cvt_pk_bf16_f32 v109, v72, v73
	v_mul_f32_e32 v18, v75, v75
	v_fmac_f32_e32 v18, v74, v74
	v_fmac_f32_e32 v18, v76, v76
	v_fmac_f32_e32 v18, v77, v77
	v_add_f32_e32 v0, v0, v18
	v_cvt_pk_bf16_f32 v110, v74, v75
	v_cvt_pk_bf16_f32 v111, v76, v77
	v_mul_f32_e32 v18, v79, v79
	v_fmac_f32_e32 v18, v78, v78
	v_fmac_f32_e32 v18, v80, v80
	v_fmac_f32_e32 v18, v81, v81
	v_add_f32_e32 v0, v0, v18
	v_cvt_pk_bf16_f32 v112, v78, v79
	v_cvt_pk_bf16_f32 v113, v80, v81
	v_mov_b32_e32 v115, 0
	v_lshlrev_b64 v[100:101], 11, v[114:115]
	v_lshl_add_u64 v[100:101], v[4:5], 0, v[100:101]
	global_store_dwordx2 v[100:101], v[106:107], off
	global_store_dwordx2 v[100:101], v[108:109], off offset:512
	global_store_dwordx2 v[100:101], v[110:111], off offset:1024
	global_store_dwordx2 v[100:101], v[112:113], off offset:1536
	ds_bpermute_b32 v16, v10, v0
	s_waitcnt lgkmcnt(0)
	v_add_f32_e32 v0, v0, v16
	ds_bpermute_b32 v16, v11, v0
	s_waitcnt lgkmcnt(0)
	v_add_f32_e32 v0, v0, v16
	ds_bpermute_b32 v16, v12, v0
	s_waitcnt lgkmcnt(0)
	v_add_f32_e32 v0, v0, v16
	ds_bpermute_b32 v16, v13, v0
	s_waitcnt lgkmcnt(0)
	v_add_f32_e32 v0, v0, v16
	ds_bpermute_b32 v16, v14, v0
	s_waitcnt lgkmcnt(0)
	v_add_f32_e32 v0, v0, v16
	ds_bpermute_b32 v16, v15, v0
	s_waitcnt lgkmcnt(0)
	v_add_f32_e32 v0, v0, v16
	v_lshlrev_b64 v[102:103], 6, v[114:115]
	v_cndmask_b32_e64 v0, 0, v0, s[36:37]
	v_lshl_add_u64 v[102:103], v[6:7], 0, v[102:103]
	s_and_saveexec_b64 s[6:7], vcc
	global_store_dword v[102:103], v0, off
	s_or_b64 exec, exec, s[6:7]
	v_add_u32_e32 v114, s8, v114
	s_waitcnt vmcnt(20)
	v_mul_f32_e32 v0, v83, v83
	v_fmac_f32_e32 v0, v82, v82
	v_fmac_f32_e32 v0, v84, v84
	v_fmac_f32_e32 v0, v85, v85
	v_cvt_pk_bf16_f32 v106, v82, v83
	v_cvt_pk_bf16_f32 v107, v84, v85
	v_mul_f32_e32 v18, v87, v87
	v_fmac_f32_e32 v18, v86, v86
	v_fmac_f32_e32 v18, v88, v88
	v_fmac_f32_e32 v18, v89, v89
	v_add_f32_e32 v0, v0, v18
	v_cvt_pk_bf16_f32 v108, v86, v87
	v_cvt_pk_bf16_f32 v109, v88, v89
	v_mul_f32_e32 v18, v91, v91
	v_fmac_f32_e32 v18, v90, v90
	v_fmac_f32_e32 v18, v92, v92
	v_fmac_f32_e32 v18, v93, v93
	v_add_f32_e32 v0, v0, v18
	v_cvt_pk_bf16_f32 v110, v90, v91
	v_cvt_pk_bf16_f32 v111, v92, v93
	v_mul_f32_e32 v18, v95, v95
	v_fmac_f32_e32 v18, v94, v94
	v_fmac_f32_e32 v18, v96, v96
	v_fmac_f32_e32 v18, v97, v97
	v_add_f32_e32 v0, v0, v18
	v_cvt_pk_bf16_f32 v112, v94, v95
	v_cvt_pk_bf16_f32 v113, v96, v97
	v_mov_b32_e32 v115, 0
	v_lshlrev_b64 v[100:101], 11, v[114:115]
	v_lshl_add_u64 v[100:101], v[4:5], 0, v[100:101]
	global_store_dwordx2 v[100:101], v[106:107], off
	global_store_dwordx2 v[100:101], v[108:109], off offset:512
	global_store_dwordx2 v[100:101], v[110:111], off offset:1024
	global_store_dwordx2 v[100:101], v[112:113], off offset:1536
	ds_bpermute_b32 v16, v10, v0
	s_waitcnt lgkmcnt(0)
	v_add_f32_e32 v0, v0, v16
	ds_bpermute_b32 v16, v11, v0
	s_waitcnt lgkmcnt(0)
	v_add_f32_e32 v0, v0, v16
	ds_bpermute_b32 v16, v12, v0
	s_waitcnt lgkmcnt(0)
	v_add_f32_e32 v0, v0, v16
	ds_bpermute_b32 v16, v13, v0
	s_waitcnt lgkmcnt(0)
	v_add_f32_e32 v0, v0, v16
	ds_bpermute_b32 v16, v14, v0
	s_waitcnt lgkmcnt(0)
	v_add_f32_e32 v0, v0, v16
	ds_bpermute_b32 v16, v15, v0
	s_waitcnt lgkmcnt(0)
	v_add_f32_e32 v0, v0, v16
	v_lshlrev_b64 v[102:103], 6, v[114:115]
	v_cndmask_b32_e64 v0, 0, v0, s[36:37]
	v_lshl_add_u64 v[102:103], v[6:7], 0, v[102:103]
	s_and_saveexec_b64 s[6:7], vcc
	global_store_dword v[102:103], v0, off
	s_or_b64 exec, exec, s[6:7]
